# P5: non-temporal hint on the read-once gate (z) loads
# speedup vs baseline: 1.0041x; 1.0033x over previous
.LBB0_486:
	s_waitcnt vmcnt(0)
	v_lshrrev_b32_e32 v51, 2, v170
	s_or_b32 s6, s72, s26
	v_and_b32_e32 v50, 16, v170
	v_and_b32_e32 v51, 8, v51
	v_or3_b32 v128, v50, v51, s31
	v_or_b32_e32 v136, s6, v169
	v_mov_b64_e32 v[50:51], s[12:13]
	v_ashrrev_i32_e32 v129, 31, v128
	v_mad_i64_i32 v[52:53], s[6:7], v136, s66, v[50:51]
	s_lshl_b32 s26, s73, 1
	v_lshl_add_u64 v[52:53], v[52:53], 0, s[26:27]
	v_lshlrev_b64 v[54:55], 1, v[128:129]
	v_lshl_add_u64 v[52:53], v[52:53], 0, v[54:55]
	v_or_b32_e32 v132, 16, v136
	global_load_dwordx4 v[118:121], v[52:53], off offset:2048 nt
	global_load_dwordx4 v[114:117], v[52:53], off offset:2112 nt
	v_mad_i64_i32 v[52:53], s[6:7], v132, s66, v[50:51]
	v_lshl_add_u64 v[52:53], v[52:53], 0, s[26:27]
	v_lshl_add_u64 v[52:53], v[52:53], 0, v[54:55]
	v_or_b32_e32 v126, 32, v136
	v_or_b32_e32 v122, 48, v136
	global_load_dwordx4 v[110:113], v[52:53], off offset:2048 nt
	global_load_dwordx4 v[82:85], v[52:53], off offset:2112 nt
	v_mad_i64_i32 v[52:53], s[6:7], v126, s66, v[50:51]
	v_mad_i64_i32 v[50:51], s[6:7], v122, s66, v[50:51]
	v_lshl_add_u64 v[52:53], v[52:53], 0, s[26:27]
	v_lshl_add_u64 v[50:51], v[50:51], 0, s[26:27]
	v_lshl_add_u64 v[52:53], v[52:53], 0, v[54:55]
	v_lshl_add_u64 v[50:51], v[50:51], 0, v[54:55]
	global_load_dwordx4 v[62:65], v[52:53], off offset:2048 nt
	global_load_dwordx4 v[58:61], v[52:53], off offset:2112 nt
	global_load_dwordx4 v[54:57], v[50:51], off offset:2048 nt
	s_nop 0
	global_load_dwordx4 v[50:53], v[50:51], off offset:2112 nt
	s_add_i32 s33, s33, 1
	s_cmp_ge_i32 s33, s35
	s_cselect_b64 s[10:11], -1, 0
	s_and_b64 vcc, exec, s[10:11]
	s_cbranch_vccnz .LBB0_488
	v_mov_b32_e32 v20, v168
	s_and_b32 s6, s60, 0xffffff00
	s_and_b32 s7, s61, 0xc0
	s_or_b32 s6, s6, s7
	v_ashrrev_i32_e32 v18, 4, v20
	v_add_u32_e32 v21, s6, v18
	v_mov_b64_e32 v[18:19], s[12:13]
	v_mad_i64_i32 v[18:19], s[6:7], v21, s66, v[18:19]
	s_and_b32 s6, s62, 0x180
	s_lshl_b32 s6, s6, 1
	s_mov_b32 s7, s27
	v_lshlrev_b32_e32 v20, 4, v20
	v_lshl_add_u64 v[18:19], v[18:19], 0, s[6:7]
	v_and_b32_e32 v162, 0xf0, v20
	v_lshl_add_u64 v[18:19], v[18:19], 0, v[162:163]
	v_add_co_u32_e32 v20, vcc, 0x30000, v18
	s_nop 1
	v_addc_co_u32_e32 v21, vcc, 0, v19, vcc
	global_load_dwordx4 v[22:25], v[18:19], off
	s_nop 0
	global_load_dwordx4 v[18:21], v[20:21], off
